# P0 weight-transpose items: all 16 row loads of an item issued together (counted vmcnt) instead of 16 serial round trips; on top of rings + P0 row-loop wait fix
# speedup vs baseline: 1.0030x; 1.0030x over previous
; #define LAS __attribute__((address_space(3)))
; __device__ __forceinline__ unsigned pk2(float lo, float hi) { return pg8::cvt_pk_bf16(lo, hi); }
; __device__ __forceinline__ void transpose_item(const float* W, int ldw, int K, const float* gain, bf16* WT, int kb, int scol0, int drow0, LAS float* scr, int lane) {
;     const int k0 = 64 * kb;
; #pragma unroll 4
;     for (int i = 0; i < 16; ++i) { const int kk = 4 * i + (lane >> 4); f32x4 w = *(const f32x4*)(W + (size_t)(k0 + kk) * ldw + scol0 + 4 * (lane & 15)); if (gain) w = w * gain[k0 + kk];
;         LAS float* d = scr + kk * 65 + 4 * (lane & 15); d[0] = w[0]; d[1] = w[1]; d[2] = w[2]; d[3] = w[3]; }
;     asm volatile("s_waitcnt lgkmcnt(0)" ::: "memory");
;     const int c = lane & 7;
; #pragma unroll
;     for (int j = 0; j < 8; ++j) { const int n = (lane >> 3) + 8 * j; const LAS float* p = scr + (8 * c) * 65 + n;
;         v4u o; o.x = pk2(p[0 * 65], p[1 * 65]); o.y = pk2(p[2 * 65], p[3 * 65]); o.z = pk2(p[4 * 65], p[5 * 65]); o.w = pk2(p[6 * 65], p[7 * 65]);
;         *(v4u*)(WT + (size_t)(drow0 + n) * K + k0 + 8 * c) = o; }
.LBB0_23:
	v_lshl_add_u64 v[34:35], v[12:13], 0, s[34:35]
	global_load_dwordx4 v[44:47], v[34:35], off
	v_lshl_add_u64 v[34:35], v[10:11], 0, s[34:35]
	global_load_dwordx4 v[48:51], v[34:35], off
	v_lshl_add_u64 v[34:35], v[8:9], 0, s[34:35]
	global_load_dwordx4 v[52:55], v[34:35], off
	v_lshl_add_u64 v[34:35], v[6:7], 0, s[34:35]
	global_load_dwordx4 v[56:59], v[34:35], off
	s_add_u32 s34, s34, 0x20000
	s_addc_u32 s35, s35, 0
	v_lshl_add_u64 v[34:35], v[12:13], 0, s[34:35]
	global_load_dwordx4 v[60:63], v[34:35], off
	v_lshl_add_u64 v[34:35], v[10:11], 0, s[34:35]
	global_load_dwordx4 v[64:67], v[34:35], off
	v_lshl_add_u64 v[34:35], v[8:9], 0, s[34:35]
	global_load_dwordx4 v[68:71], v[34:35], off
	v_lshl_add_u64 v[34:35], v[6:7], 0, s[34:35]
	global_load_dwordx4 v[72:75], v[34:35], off
	s_add_u32 s34, s34, 0x20000
	s_addc_u32 s35, s35, 0
	v_lshl_add_u64 v[34:35], v[12:13], 0, s[34:35]
	global_load_dwordx4 v[76:79], v[34:35], off
	v_lshl_add_u64 v[34:35], v[10:11], 0, s[34:35]
	global_load_dwordx4 v[80:83], v[34:35], off
	v_lshl_add_u64 v[34:35], v[8:9], 0, s[34:35]
	global_load_dwordx4 v[84:87], v[34:35], off
	v_lshl_add_u64 v[34:35], v[6:7], 0, s[34:35]
	global_load_dwordx4 v[88:91], v[34:35], off
	s_add_u32 s34, s34, 0x20000
	s_addc_u32 s35, s35, 0
	v_lshl_add_u64 v[34:35], v[12:13], 0, s[34:35]
	global_load_dwordx4 v[92:95], v[34:35], off
	v_lshl_add_u64 v[34:35], v[10:11], 0, s[34:35]
	global_load_dwordx4 v[96:99], v[34:35], off
	v_lshl_add_u64 v[34:35], v[8:9], 0, s[34:35]
	global_load_dwordx4 v[100:103], v[34:35], off
	v_lshl_add_u64 v[34:35], v[6:7], 0, s[34:35]
	global_load_dwordx4 v[104:107], v[34:35], off
	s_add_u32 s34, s34, 0x20000
	s_addc_u32 s35, s35, 0
	s_waitcnt vmcnt(12)
	v_add_u32_e32 v33, 0x410, v32
	v_add_u32_e32 v40, 0x418, v32
	ds_write2_b32 v32, v44, v45 offset1:1
	ds_write2_b32 v32, v46, v47 offset0:2 offset1:3
	ds_write2_b32 v33, v48, v49 offset1:1
	ds_write2_b32 v40, v50, v51 offset1:1
	v_add_u32_e32 v33, 0x820, v32
	v_add_u32_e32 v40, 0x828, v32
	ds_write2_b32 v33, v52, v53 offset1:1
	ds_write2_b32 v40, v54, v55 offset1:1
	v_add_u32_e32 v33, 0xc30, v32
	v_add_u32_e32 v38, 0xc38, v32
	v_add_u32_e32 v32, 0x1040, v32
	ds_write2_b32 v33, v56, v57 offset1:1
	ds_write2_b32 v38, v58, v59 offset1:1
	s_waitcnt vmcnt(8)
	v_add_u32_e32 v33, 0x410, v32
	v_add_u32_e32 v40, 0x418, v32
	ds_write2_b32 v32, v60, v61 offset1:1
	ds_write2_b32 v32, v62, v63 offset0:2 offset1:3
	ds_write2_b32 v33, v64, v65 offset1:1
	ds_write2_b32 v40, v66, v67 offset1:1
	v_add_u32_e32 v33, 0x820, v32
	v_add_u32_e32 v40, 0x828, v32
	ds_write2_b32 v33, v68, v69 offset1:1
	ds_write2_b32 v40, v70, v71 offset1:1
	v_add_u32_e32 v33, 0xc30, v32
	v_add_u32_e32 v38, 0xc38, v32
	v_add_u32_e32 v32, 0x1040, v32
	ds_write2_b32 v33, v72, v73 offset1:1
	ds_write2_b32 v38, v74, v75 offset1:1
	s_waitcnt vmcnt(4)
	v_add_u32_e32 v33, 0x410, v32
	v_add_u32_e32 v40, 0x418, v32
	ds_write2_b32 v32, v76, v77 offset1:1
	ds_write2_b32 v32, v78, v79 offset0:2 offset1:3
	ds_write2_b32 v33, v80, v81 offset1:1
	ds_write2_b32 v40, v82, v83 offset1:1
	v_add_u32_e32 v33, 0x820, v32
	v_add_u32_e32 v40, 0x828, v32
	ds_write2_b32 v33, v84, v85 offset1:1
	ds_write2_b32 v40, v86, v87 offset1:1
	v_add_u32_e32 v33, 0xc30, v32
	v_add_u32_e32 v38, 0xc38, v32
	v_add_u32_e32 v32, 0x1040, v32
	ds_write2_b32 v33, v88, v89 offset1:1
	ds_write2_b32 v38, v90, v91 offset1:1
	s_waitcnt vmcnt(0)
	v_add_u32_e32 v33, 0x410, v32
	v_add_u32_e32 v40, 0x418, v32
	ds_write2_b32 v32, v92, v93 offset1:1
	ds_write2_b32 v32, v94, v95 offset0:2 offset1:3
	ds_write2_b32 v33, v96, v97 offset1:1
	ds_write2_b32 v40, v98, v99 offset1:1
	v_add_u32_e32 v33, 0x820, v32
	v_add_u32_e32 v40, 0x828, v32
	ds_write2_b32 v33, v100, v101 offset1:1
	ds_write2_b32 v40, v102, v103 offset1:1
	v_add_u32_e32 v33, 0xc30, v32
	v_add_u32_e32 v38, 0xc38, v32
	v_add_u32_e32 v32, 0x1040, v32
	ds_write2_b32 v33, v104, v105 offset1:1
	ds_write2_b32 v38, v106, v107 offset1:1
	s_waitcnt lgkmcnt(0)
	s_lshl_b32 s10, s43, 6
	s_lshl_b32 s35, s43, 1
	s_and_b32 s34, s10, 0x7c0
	s_and_b32 s10, s35, 0x7fffffc0
	s_addk_i32 s10, 0xfb00
	s_lshl_b64 s[36:37], s[10:11], 1
	s_add_u32 s30, s30, s36
	s_waitcnt lgkmcnt(0)
	s_addc_u32 s31, s31, s37
	ds_read2_b32 v[6:7], v16 offset1:65
	v_or_b32_e32 v10, s34, v15
	v_lshl_add_u64 v[32:33], s[30:31], 0, v[0:1]
	s_waitcnt lgkmcnt(0)
	v_cvt_pk_bf16_f32 v6, v6, v7
	ds_read2_b32 v[8:9], v16 offset0:130 offset1:195
	v_mov_b32_e32 v11, v1
	v_lshlrev_b32_e32 v10, 11, v10
	v_lshl_add_u64 v[32:33], v[32:33], 0, s[28:29]
	s_waitcnt lgkmcnt(0)
; #define LAS __attribute__((address_space(3)))
; __device__ __forceinline__ unsigned pk2(float lo, float hi) { return pg8::cvt_pk_bf16(lo, hi); }
; __device__ __forceinline__ void transpose_item(const float* W, int ldw, int K, const float* gain, bf16* WT, int kb, int scol0, int drow0, LAS float* scr, int lane) {
;     ...
;     const int c = lane & 7;
; #pragma unroll
;     for (int j = 0; j < 8; ++j) { const int n = (lane >> 3) + 8 * j; const LAS float* p = scr + (8 * c) * 65 + n;
;         v4u o; o.x = pk2(p[0 * 65], p[1 * 65]); o.y = pk2(p[2 * 65], p[3 * 65]); o.z = pk2(p[4 * 65], p[5 * 65]); o.w = pk2(p[6 * 65], p[7 * 65]);
;         *(v4u*)(WT + (size_t)(drow0 + n) * K + k0 + 8 * c) = o; }
;     asm volatile("s_waitcnt lgkmcnt(0)" ::: "memory");
	v_cvt_pk_bf16_f32 v7, v8, v9
	ds_read2_b32 v[8:9], v31 offset0:4 offset1:69
	v_lshl_add_u64 v[10:11], v[32:33], 0, v[10:11]
	s_waitcnt lgkmcnt(0)
	v_cvt_pk_bf16_f32 v8, v8, v9
	ds_read2_b32 v[12:13], v31 offset0:134 offset1:199
	s_waitcnt lgkmcnt(0)
	v_cvt_pk_bf16_f32 v9, v12, v13
	flat_store_dwordx4 v[10:11], v[6:9]
	ds_read2_b32 v[6:7], v16 offset0:8 offset1:73
	v_mov_b32_e32 v13, v1
	s_waitcnt lgkmcnt(0)
	v_cvt_pk_bf16_f32 v6, v6, v7
	ds_read2_b32 v[8:9], v16 offset0:138 offset1:203
	s_waitcnt lgkmcnt(0)
	v_cvt_pk_bf16_f32 v7, v8, v9
	ds_read2_b32 v[8:9], v31 offset0:12 offset1:77
	s_waitcnt lgkmcnt(0)
	v_cvt_pk_bf16_f32 v8, v8, v9
	v_or_b32_e32 v9, s34, v18
	v_lshlrev_b32_e32 v12, 11, v9
	v_lshl_add_u64 v[12:13], v[32:33], 0, v[12:13]
	ds_read2_b32 v[10:11], v31 offset0:142 offset1:207
	s_waitcnt lgkmcnt(0)
	v_cvt_pk_bf16_f32 v9, v10, v11
	flat_store_dwordx4 v[12:13], v[6:9]
	ds_read2_b32 v[6:7], v16 offset0:16 offset1:81
	v_mov_b32_e32 v13, v1
	s_waitcnt lgkmcnt(0)
	v_cvt_pk_bf16_f32 v6, v6, v7
	ds_read2_b32 v[8:9], v16 offset0:146 offset1:211
	s_waitcnt lgkmcnt(0)
	v_cvt_pk_bf16_f32 v7, v8, v9
	ds_read2_b32 v[8:9], v31 offset0:20 offset1:85
	s_waitcnt lgkmcnt(0)
	v_cvt_pk_bf16_f32 v8, v8, v9
	v_or_b32_e32 v9, s34, v19
	v_lshlrev_b32_e32 v12, 11, v9
	v_lshl_add_u64 v[12:13], v[32:33], 0, v[12:13]
	ds_read2_b32 v[10:11], v31 offset0:150 offset1:215
	s_waitcnt lgkmcnt(0)
	v_cvt_pk_bf16_f32 v9, v10, v11
	flat_store_dwordx4 v[12:13], v[6:9]
	ds_read2_b32 v[6:7], v16 offset0:24 offset1:89
	v_mov_b32_e32 v13, v1
	s_waitcnt lgkmcnt(0)
	v_cvt_pk_bf16_f32 v6, v6, v7
	ds_read2_b32 v[8:9], v16 offset0:154 offset1:219
	s_waitcnt lgkmcnt(0)
	v_cvt_pk_bf16_f32 v7, v8, v9
	ds_read2_b32 v[8:9], v31 offset0:28 offset1:93
	s_waitcnt lgkmcnt(0)
	v_cvt_pk_bf16_f32 v8, v8, v9
	v_or_b32_e32 v9, s34, v21
	v_lshlrev_b32_e32 v12, 11, v9
	v_lshl_add_u64 v[12:13], v[32:33], 0, v[12:13]
	ds_read2_b32 v[10:11], v31 offset0:158 offset1:223
	s_waitcnt lgkmcnt(0)
	v_cvt_pk_bf16_f32 v9, v10, v11
	flat_store_dwordx4 v[12:13], v[6:9]
	ds_read2_b32 v[6:7], v16 offset0:32 offset1:97
	v_mov_b32_e32 v13, v1
	s_waitcnt lgkmcnt(0)
	v_cvt_pk_bf16_f32 v6, v6, v7
	ds_read2_b32 v[8:9], v16 offset0:162 offset1:227
	s_waitcnt lgkmcnt(0)
	v_cvt_pk_bf16_f32 v7, v8, v9
	ds_read2_b32 v[8:9], v31 offset0:36 offset1:101
	s_waitcnt lgkmcnt(0)
	v_cvt_pk_bf16_f32 v8, v8, v9
	v_or_b32_e32 v9, s34, v22
	v_lshlrev_b32_e32 v12, 11, v9
	v_lshl_add_u64 v[12:13], v[32:33], 0, v[12:13]
	ds_read2_b32 v[10:11], v31 offset0:166 offset1:231
	s_waitcnt lgkmcnt(0)
	v_cvt_pk_bf16_f32 v9, v10, v11
	flat_store_dwordx4 v[12:13], v[6:9]
	ds_read2_b32 v[6:7], v16 offset0:40 offset1:105
	v_mov_b32_e32 v13, v1
	s_waitcnt lgkmcnt(0)
	v_cvt_pk_bf16_f32 v6, v6, v7
	ds_read2_b32 v[8:9], v16 offset0:170 offset1:235
	s_waitcnt lgkmcnt(0)
	v_cvt_pk_bf16_f32 v7, v8, v9
	ds_read2_b32 v[8:9], v31 offset0:44 offset1:109
	s_waitcnt lgkmcnt(0)
	v_cvt_pk_bf16_f32 v8, v8, v9
	v_or_b32_e32 v9, s34, v23
	v_lshlrev_b32_e32 v12, 11, v9
	v_lshl_add_u64 v[12:13], v[32:33], 0, v[12:13]
	ds_read2_b32 v[10:11], v31 offset0:174 offset1:239
	s_waitcnt lgkmcnt(0)
	v_cvt_pk_bf16_f32 v9, v10, v11
	flat_store_dwordx4 v[12:13], v[6:9]
	ds_read2_b32 v[6:7], v16 offset0:48 offset1:113
	v_mov_b32_e32 v13, v1
	s_waitcnt lgkmcnt(0)
	v_cvt_pk_bf16_f32 v6, v6, v7
	ds_read2_b32 v[8:9], v16 offset0:178 offset1:243
	s_waitcnt lgkmcnt(0)
	v_cvt_pk_bf16_f32 v7, v8, v9
	ds_read2_b32 v[8:9], v31 offset0:52 offset1:117
	s_waitcnt lgkmcnt(0)
	v_cvt_pk_bf16_f32 v8, v8, v9
	v_or_b32_e32 v9, s34, v24
	v_lshlrev_b32_e32 v12, 11, v9
	v_lshl_add_u64 v[12:13], v[32:33], 0, v[12:13]
	ds_read2_b32 v[10:11], v31 offset0:182 offset1:247
	s_waitcnt lgkmcnt(0)
	v_cvt_pk_bf16_f32 v9, v10, v11
	flat_store_dwordx4 v[12:13], v[6:9]
	ds_read2_b32 v[6:7], v16 offset0:56 offset1:121
	v_mov_b32_e32 v13, v1
	s_waitcnt lgkmcnt(0)
	v_cvt_pk_bf16_f32 v6, v6, v7
	ds_read2_b32 v[8:9], v16 offset0:186 offset1:251
	s_waitcnt lgkmcnt(0)
	v_cvt_pk_bf16_f32 v7, v8, v9
	ds_read2_b32 v[8:9], v31 offset0:60 offset1:125
	s_waitcnt lgkmcnt(0)
	v_cvt_pk_bf16_f32 v8, v8, v9
	v_or_b32_e32 v9, s34, v25
	ds_read2_b32 v[10:11], v31 offset0:190 offset1:255
	v_lshlrev_b32_e32 v12, 11, v9
	s_waitcnt lgkmcnt(0)
	v_cvt_pk_bf16_f32 v9, v10, v11
	v_lshl_add_u64 v[10:11], v[32:33], 0, v[12:13]
	flat_store_dwordx4 v[10:11], v[6:9]
	s_waitcnt lgkmcnt(0)
	s_mov_b64 s[30:31], 0

; #define LAS __attribute__((address_space(3)))
; __device__ __forceinline__ unsigned pk2(float lo, float hi) { return pg8::cvt_pk_bf16(lo, hi); }
; __device__ __forceinline__ void transpose_item(const float* W, int ldw, int K, const float* gain, bf16* WT, int kb, int scol0, int drow0, LAS float* scr, int lane) {
;     const int k0 = 64 * kb;
; #pragma unroll 4
;     for (int i = 0; i < 16; ++i) { const int kk = 4 * i + (lane >> 4); f32x4 w = *(const f32x4*)(W + (size_t)(k0 + kk) * ldw + scol0 + 4 * (lane & 15)); if (gain) w = w * gain[k0 + kk];
;         LAS float* d = scr + kk * 65 + 4 * (lane & 15); d[0] = w[0]; d[1] = w[1]; d[2] = w[2]; d[3] = w[3]; }
;     asm volatile("s_waitcnt lgkmcnt(0)" ::: "memory");
;     const int c = lane & 7;
; #pragma unroll
;     for (int j = 0; j < 8; ++j) { const int n = (lane >> 3) + 8 * j; const LAS float* p = scr + (8 * c) * 65 + n;
;         v4u o; o.x = pk2(p[0 * 65], p[1 * 65]); o.y = pk2(p[2 * 65], p[3 * 65]); o.z = pk2(p[4 * 65], p[5 * 65]); o.w = pk2(p[6 * 65], p[7 * 65]);
;         *(v4u*)(WT + (size_t)(drow0 + n) * K + k0 + 8 * c) = o; }
.LBB0_29:
	v_mov_b32_e32 v32, v8
	v_mad_i64_i32 v[32:33], s[36:37], v32, s42, v[6:7]
	global_load_dwordx4 v[44:47], v[32:33], off
	v_add_u32_e32 v32, 4, v8
	v_mad_i64_i32 v[32:33], s[36:37], v32, s42, v[6:7]
	global_load_dwordx4 v[48:51], v[32:33], off
	v_add_u32_e32 v32, 8, v8
	v_mad_i64_i32 v[32:33], s[36:37], v32, s42, v[6:7]
	global_load_dwordx4 v[52:55], v[32:33], off
	v_add_u32_e32 v32, 12, v8
	v_mad_i64_i32 v[32:33], s[36:37], v32, s42, v[6:7]
	global_load_dwordx4 v[56:59], v[32:33], off
	v_add_u32_e32 v32, 16, v8
	v_mad_i64_i32 v[32:33], s[36:37], v32, s42, v[6:7]
	global_load_dwordx4 v[60:63], v[32:33], off
	v_add_u32_e32 v32, 20, v8
	v_mad_i64_i32 v[32:33], s[36:37], v32, s42, v[6:7]
	global_load_dwordx4 v[64:67], v[32:33], off
	v_add_u32_e32 v32, 24, v8
	v_mad_i64_i32 v[32:33], s[36:37], v32, s42, v[6:7]
	global_load_dwordx4 v[68:71], v[32:33], off
	v_add_u32_e32 v32, 28, v8
	v_mad_i64_i32 v[32:33], s[36:37], v32, s42, v[6:7]
	global_load_dwordx4 v[72:75], v[32:33], off
	v_add_u32_e32 v32, 32, v8
	v_mad_i64_i32 v[32:33], s[36:37], v32, s42, v[6:7]
	global_load_dwordx4 v[76:79], v[32:33], off
	v_add_u32_e32 v32, 36, v8
	v_mad_i64_i32 v[32:33], s[36:37], v32, s42, v[6:7]
	global_load_dwordx4 v[80:83], v[32:33], off
	v_add_u32_e32 v32, 40, v8
	v_mad_i64_i32 v[32:33], s[36:37], v32, s42, v[6:7]
	global_load_dwordx4 v[84:87], v[32:33], off
	v_add_u32_e32 v32, 44, v8
	v_mad_i64_i32 v[32:33], s[36:37], v32, s42, v[6:7]
	global_load_dwordx4 v[88:91], v[32:33], off
	v_add_u32_e32 v32, 48, v8
	v_mad_i64_i32 v[32:33], s[36:37], v32, s42, v[6:7]
	global_load_dwordx4 v[92:95], v[32:33], off
	v_add_u32_e32 v32, 52, v8
	v_mad_i64_i32 v[32:33], s[36:37], v32, s42, v[6:7]
	global_load_dwordx4 v[96:99], v[32:33], off
	v_add_u32_e32 v32, 56, v8
	v_mad_i64_i32 v[32:33], s[36:37], v32, s42, v[6:7]
	global_load_dwordx4 v[100:103], v[32:33], off
	v_add_u32_e32 v32, 60, v8
	v_mad_i64_i32 v[32:33], s[36:37], v32, s42, v[6:7]
	global_load_dwordx4 v[104:107], v[32:33], off
	s_mov_b32 s35, 64
	s_waitcnt vmcnt(12)
	v_add_u32_e32 v35, 0x410, v9
	v_add_u32_e32 v36, 0x418, v9
	ds_write2_b32 v9, v44, v45 offset1:1
	ds_write2_b32 v9, v46, v47 offset0:2 offset1:3
	ds_write2_b32 v35, v48, v49 offset1:1
	ds_write2_b32 v36, v50, v51 offset1:1
	v_add_u32_e32 v35, 0x820, v9
	v_add_u32_e32 v36, 0x828, v9
	ds_write2_b32 v35, v52, v53 offset1:1
	ds_write2_b32 v36, v54, v55 offset1:1
	v_add_u32_e32 v32, 0xc30, v9
	v_add_u32_e32 v33, 0xc38, v9
	v_add_u32_e32 v9, 0x1040, v9
	ds_write2_b32 v32, v56, v57 offset1:1
	ds_write2_b32 v33, v58, v59 offset1:1
	s_waitcnt vmcnt(8)
	v_add_u32_e32 v35, 0x410, v9
	v_add_u32_e32 v36, 0x418, v9
	ds_write2_b32 v9, v60, v61 offset1:1
	ds_write2_b32 v9, v62, v63 offset0:2 offset1:3
	ds_write2_b32 v35, v64, v65 offset1:1
	ds_write2_b32 v36, v66, v67 offset1:1
	v_add_u32_e32 v35, 0x820, v9
	v_add_u32_e32 v36, 0x828, v9
	ds_write2_b32 v35, v68, v69 offset1:1
	ds_write2_b32 v36, v70, v71 offset1:1
	v_add_u32_e32 v32, 0xc30, v9
	v_add_u32_e32 v33, 0xc38, v9
	v_add_u32_e32 v9, 0x1040, v9
	ds_write2_b32 v32, v72, v73 offset1:1
	ds_write2_b32 v33, v74, v75 offset1:1
	s_waitcnt vmcnt(4)
	v_add_u32_e32 v35, 0x410, v9
	v_add_u32_e32 v36, 0x418, v9
	ds_write2_b32 v9, v76, v77 offset1:1
	ds_write2_b32 v9, v78, v79 offset0:2 offset1:3
	ds_write2_b32 v35, v80, v81 offset1:1
	ds_write2_b32 v36, v82, v83 offset1:1
	v_add_u32_e32 v35, 0x820, v9
	v_add_u32_e32 v36, 0x828, v9
	ds_write2_b32 v35, v84, v85 offset1:1
	ds_write2_b32 v36, v86, v87 offset1:1
	v_add_u32_e32 v32, 0xc30, v9
	v_add_u32_e32 v33, 0xc38, v9
	v_add_u32_e32 v9, 0x1040, v9
	ds_write2_b32 v32, v88, v89 offset1:1
	ds_write2_b32 v33, v90, v91 offset1:1
	s_waitcnt vmcnt(0)
	v_add_u32_e32 v35, 0x410, v9
	v_add_u32_e32 v36, 0x418, v9
	ds_write2_b32 v9, v92, v93 offset1:1
	ds_write2_b32 v9, v94, v95 offset0:2 offset1:3
	ds_write2_b32 v35, v96, v97 offset1:1
	ds_write2_b32 v36, v98, v99 offset1:1
	v_add_u32_e32 v35, 0x820, v9
	v_add_u32_e32 v36, 0x828, v9
	ds_write2_b32 v35, v100, v101 offset1:1
	ds_write2_b32 v36, v102, v103 offset1:1
	v_add_u32_e32 v32, 0xc30, v9
	v_add_u32_e32 v33, 0xc38, v9
	v_add_u32_e32 v9, 0x1040, v9
	ds_write2_b32 v32, v104, v105 offset1:1
	ds_write2_b32 v33, v106, v107 offset1:1
	s_waitcnt lgkmcnt(0)
	s_ashr_i32 s35, s34, 31
	s_waitcnt lgkmcnt(0)
	s_lshl_b64 s[34:35], s[34:35], 1
	ds_read2_b32 v[6:7], v16 offset1:65
	v_add_u32_e32 v10, s10, v15
	s_add_u32 s30, s30, s34
	s_waitcnt lgkmcnt(0)
	v_cvt_pk_bf16_f32 v6, v6, v7
	ds_read2_b32 v[8:9], v16 offset0:130 offset1:195
	v_ashrrev_i32_e32 v11, 31, v10
	s_addc_u32 s31, s31, s35
	s_waitcnt lgkmcnt(0)
; #define LAS __attribute__((address_space(3)))
; __device__ __forceinline__ unsigned pk2(float lo, float hi) { return pg8::cvt_pk_bf16(lo, hi); }
; __device__ __forceinline__ void transpose_item(const float* W, int ldw, int K, const float* gain, bf16* WT, int kb, int scol0, int drow0, LAS float* scr, int lane) {
;     ...
;     const int c = lane & 7;
; #pragma unroll
;     for (int j = 0; j < 8; ++j) { const int n = (lane >> 3) + 8 * j; const LAS float* p = scr + (8 * c) * 65 + n;
;         v4u o; o.x = pk2(p[0 * 65], p[1 * 65]); o.y = pk2(p[2 * 65], p[3 * 65]); o.z = pk2(p[4 * 65], p[5 * 65]); o.w = pk2(p[6 * 65], p[7 * 65]);
;         *(v4u*)(WT + (size_t)(drow0 + n) * K + k0 + 8 * c) = o; }
;     asm volatile("s_waitcnt lgkmcnt(0)" ::: "memory");
; }
	v_cvt_pk_bf16_f32 v7, v8, v9
	ds_read2_b32 v[8:9], v31 offset0:4 offset1:69
	v_lshlrev_b64 v[10:11], 11, v[10:11]
	v_lshl_add_u64 v[32:33], s[30:31], 0, v[0:1]
	s_waitcnt lgkmcnt(0)
	v_cvt_pk_bf16_f32 v8, v8, v9
	ds_read2_b32 v[12:13], v31 offset0:134 offset1:199
	v_lshl_add_u64 v[10:11], v[32:33], 0, v[10:11]
	s_waitcnt lgkmcnt(0)
	v_cvt_pk_bf16_f32 v9, v12, v13
	flat_store_dwordx4 v[10:11], v[6:9]
	v_add_u32_e32 v12, s10, v18
	ds_read2_b32 v[6:7], v16 offset0:8 offset1:73
	v_ashrrev_i32_e32 v13, 31, v12
	s_waitcnt lgkmcnt(0)
	v_cvt_pk_bf16_f32 v6, v6, v7
	ds_read2_b32 v[8:9], v16 offset0:138 offset1:203
	v_lshlrev_b64 v[12:13], 11, v[12:13]
	s_waitcnt lgkmcnt(0)
	v_cvt_pk_bf16_f32 v7, v8, v9
	ds_read2_b32 v[8:9], v31 offset0:12 offset1:77
	v_lshl_add_u64 v[12:13], v[32:33], 0, v[12:13]
	s_waitcnt lgkmcnt(0)
	v_cvt_pk_bf16_f32 v8, v8, v9
	ds_read2_b32 v[10:11], v31 offset0:142 offset1:207
	s_waitcnt lgkmcnt(0)
	v_cvt_pk_bf16_f32 v9, v10, v11
	flat_store_dwordx4 v[12:13], v[6:9]
	v_add_u32_e32 v12, s10, v19
	ds_read2_b32 v[6:7], v16 offset0:16 offset1:81
	v_ashrrev_i32_e32 v13, 31, v12
	s_waitcnt lgkmcnt(0)
	v_cvt_pk_bf16_f32 v6, v6, v7
	ds_read2_b32 v[8:9], v16 offset0:146 offset1:211
	v_lshlrev_b64 v[12:13], 11, v[12:13]
	s_waitcnt lgkmcnt(0)
	v_cvt_pk_bf16_f32 v7, v8, v9
	ds_read2_b32 v[8:9], v31 offset0:20 offset1:85
	v_lshl_add_u64 v[12:13], v[32:33], 0, v[12:13]
	s_waitcnt lgkmcnt(0)
	v_cvt_pk_bf16_f32 v8, v8, v9
	ds_read2_b32 v[10:11], v31 offset0:150 offset1:215
	s_waitcnt lgkmcnt(0)
	v_cvt_pk_bf16_f32 v9, v10, v11
	flat_store_dwordx4 v[12:13], v[6:9]
	v_add_u32_e32 v12, s10, v21
	ds_read2_b32 v[6:7], v16 offset0:24 offset1:89
	v_ashrrev_i32_e32 v13, 31, v12
	s_waitcnt lgkmcnt(0)
	v_cvt_pk_bf16_f32 v6, v6, v7
	ds_read2_b32 v[8:9], v16 offset0:154 offset1:219
	v_lshlrev_b64 v[12:13], 11, v[12:13]
	s_waitcnt lgkmcnt(0)
	v_cvt_pk_bf16_f32 v7, v8, v9
	ds_read2_b32 v[8:9], v31 offset0:28 offset1:93
	v_lshl_add_u64 v[12:13], v[32:33], 0, v[12:13]
	s_waitcnt lgkmcnt(0)
	v_cvt_pk_bf16_f32 v8, v8, v9
	ds_read2_b32 v[10:11], v31 offset0:158 offset1:223
	s_waitcnt lgkmcnt(0)
	v_cvt_pk_bf16_f32 v9, v10, v11
	flat_store_dwordx4 v[12:13], v[6:9]
	v_add_u32_e32 v12, s10, v22
	ds_read2_b32 v[6:7], v16 offset0:32 offset1:97
	v_ashrrev_i32_e32 v13, 31, v12
	s_waitcnt lgkmcnt(0)
	v_cvt_pk_bf16_f32 v6, v6, v7
	ds_read2_b32 v[8:9], v16 offset0:162 offset1:227
	v_lshlrev_b64 v[12:13], 11, v[12:13]
	s_waitcnt lgkmcnt(0)
	v_cvt_pk_bf16_f32 v7, v8, v9
	ds_read2_b32 v[8:9], v31 offset0:36 offset1:101
	v_lshl_add_u64 v[12:13], v[32:33], 0, v[12:13]
	s_waitcnt lgkmcnt(0)
	v_cvt_pk_bf16_f32 v8, v8, v9
	ds_read2_b32 v[10:11], v31 offset0:166 offset1:231
	s_waitcnt lgkmcnt(0)
	v_cvt_pk_bf16_f32 v9, v10, v11
	flat_store_dwordx4 v[12:13], v[6:9]
	v_add_u32_e32 v12, s10, v23
	ds_read2_b32 v[6:7], v16 offset0:40 offset1:105
	v_ashrrev_i32_e32 v13, 31, v12
	s_waitcnt lgkmcnt(0)
	v_cvt_pk_bf16_f32 v6, v6, v7
	ds_read2_b32 v[8:9], v16 offset0:170 offset1:235
	v_lshlrev_b64 v[12:13], 11, v[12:13]
	s_waitcnt lgkmcnt(0)
	v_cvt_pk_bf16_f32 v7, v8, v9
	ds_read2_b32 v[8:9], v31 offset0:44 offset1:109
	v_lshl_add_u64 v[12:13], v[32:33], 0, v[12:13]
	s_waitcnt lgkmcnt(0)
	v_cvt_pk_bf16_f32 v8, v8, v9
	ds_read2_b32 v[10:11], v31 offset0:174 offset1:239
	s_waitcnt lgkmcnt(0)
	v_cvt_pk_bf16_f32 v9, v10, v11
	flat_store_dwordx4 v[12:13], v[6:9]
	v_add_u32_e32 v12, s10, v24
	ds_read2_b32 v[6:7], v16 offset0:48 offset1:113
	v_ashrrev_i32_e32 v13, 31, v12
	s_waitcnt lgkmcnt(0)
	v_cvt_pk_bf16_f32 v6, v6, v7
	ds_read2_b32 v[8:9], v16 offset0:178 offset1:243
	v_lshlrev_b64 v[12:13], 11, v[12:13]
	s_waitcnt lgkmcnt(0)
	v_cvt_pk_bf16_f32 v7, v8, v9
	ds_read2_b32 v[8:9], v31 offset0:52 offset1:117
	v_lshl_add_u64 v[12:13], v[32:33], 0, v[12:13]
	s_waitcnt lgkmcnt(0)
	v_cvt_pk_bf16_f32 v8, v8, v9
	ds_read2_b32 v[10:11], v31 offset0:182 offset1:247
	s_waitcnt lgkmcnt(0)
	v_cvt_pk_bf16_f32 v9, v10, v11
	flat_store_dwordx4 v[12:13], v[6:9]
	ds_read2_b32 v[6:7], v16 offset0:56 offset1:121
	v_add_u32_e32 v12, s10, v25
	s_waitcnt lgkmcnt(0)
	v_cvt_pk_bf16_f32 v6, v6, v7
	ds_read2_b32 v[8:9], v16 offset0:186 offset1:251
	s_waitcnt lgkmcnt(0)
	v_cvt_pk_bf16_f32 v7, v8, v9
	ds_read2_b32 v[8:9], v31 offset0:60 offset1:125
	v_ashrrev_i32_e32 v13, 31, v12
	s_waitcnt lgkmcnt(0)
	v_cvt_pk_bf16_f32 v8, v8, v9
	ds_read2_b32 v[10:11], v31 offset0:190 offset1:255
	v_lshlrev_b64 v[12:13], 11, v[12:13]
	s_waitcnt lgkmcnt(0)
	v_cvt_pk_bf16_f32 v9, v10, v11
	v_lshl_add_u64 v[10:11], v[32:33], 0, v[12:13]
	flat_store_dwordx4 v[10:11], v[6:9]
	s_waitcnt lgkmcnt(0)
	s_branch .LBB0_20
